# grid barrier: XCD leaders poll the top-level generation word without the sleep between polls
# speedup vs baseline: 1.0046x; 1.0046x over previous
.LBB0_662:
	s_and_b32 s20, s2, 0xff
	s_mov_b64 s[36:37], -1
	s_cmp_lg_u32 s20, 0
	s_mov_b64 s[40:41], -1
	s_sleep 0
	s_cbranch_scc1 .LBB0_665
	v_readlane_b32 s4, v254, 37
	v_readlane_b32 s5, v254, 38
	s_nop 4
	global_load_dword v0, v185, s[4:5] sc1
	s_waitcnt vmcnt(0)
	v_cmp_eq_u32_e32 vcc, 0, v0
	s_cbranch_vccnz .LBB0_667
	s_mov_b64 s[40:41], 0
	s_mov_b64 s[38:39], -1
